# gdn_scan 128-step chunk-state scans (critical path of the attention phase): per-iteration s_waitcnt vmcnt(0) drains replaced by counted waits so the three-step-ahead prefetch and the state stores stay
# speedup vs baseline: 1.0147x; 1.0063x over previous
; DI void gdn_scan(CP c, int l, int seq, int h, int mode, unsigned char* sm) {
;     ...
;     const bool samp = seq > 0; const int b = seq - 1; const int nsteps = samp ? 1 : 128; const bool amode = (mode == 3); const float uscale = amode ? 0.f : 1.f;
;     const int n0 = (mode >= 2) ? 128 : 0;
;     const int item0 = samp ? 1024 + b * 4 + h : h + 4 * n0;
;     const bf16_t* Ug = (const bf16_t*)(ws + WS_U); const bf16_t* Wg = (const bf16_t*)(ws + WS_W);
;     const bf16_t* KDTg = (const bf16_t*)(ws + WS_KDT); const float* EGL = (const float*)(ws + WS_EGL);
;     bf16_t* SNg = samp ? (bf16_t*)(ws + WS_SNS) + (size_t)(b * 4 + h) * 16384 : (amode ? (bf16_t*)(ws + WS_XA) + (size_t)h * 16384 : (bf16_t*)(ws + WS_SNP) + (size_t)(h + 4 * n0) * 16384);
;     float* sout = samp ? c->out + O_SGDN + ((size_t)(l * 32 + b) * 4 + h) * 16384 : c->out + O_PGDN + ((size_t)l * 4 + h) * 16384;
;     f32x4 Sacc[8];
; #pragma unroll
;     for (int mt = 0; mt < 8; ++mt) {
;         if (samp) { const float* sp = c->in[I_SGDN] + ((size_t)(l * 32 + b) * 4 + h) * 16384;
; #pragma unroll
;             for (int i = 0; i < 4; ++i) Sacc[mt][i] = sp[(16 * mt + 4 * fq + i) * 128 + 16 * w + fr]; }
;         else {
; #pragma unroll
;             for (int i = 0; i < 4; ++i) Sacc[mt][i] = (amode && (16 * mt + 4 * fq + i == 16 * w + fr)) ? 1.f : 0.f; }
;     }
;     const u32x4 z4 = (u32x4){0u, 0u, 0u, 0u};
;     u32x4 Pw0 = z4, Pw1 = z4, Pk0 = z4, Pk1 = z4, Qw0 = z4, Qw1 = z4, Qk0 = z4, Qk1 = z4, Pu0 = z4, Pu1 = z4, Qu0 = z4, Qu1 = z4; float Pe = 1.f, Qe = 1.f, egl = 1.f;
.LBB0_548:
	s_andn2_b64 vcc, exec, s[0:1]
	s_cbranch_vccnz .LBB0_743
	v_readlane_b32 s0, v249, 25
	v_readlane_b32 s1, v249, 26
	s_andn2_b64 vcc, exec, s[0:1]
	s_cbranch_vccnz .LBB0_628
	s_add_u32 s12, s20, 0x144c4000
	s_addc_u32 s13, s21, 0
	s_add_u32 s18, s20, 0x156c4000
	s_addc_u32 s19, s21, 0
	s_add_u32 s16, s20, 0x17ac4000
	s_addc_u32 s17, s21, 0
	s_add_u32 s8, s20, 0x195c4000
	v_readlane_b32 s0, v249, 29
	s_addc_u32 s9, s21, 0
	s_lshl_b32 s14, s0, 1
	s_add_u32 s0, s20, s14
	s_addc_u32 s1, s21, 0
	s_add_u32 s6, s0, 0x1b6c6000
	s_addc_u32 s7, s1, 0
	v_readlane_b32 s0, v253, 26
	v_mov_b32_e32 v34, v188
	s_add_u32 s0, s20, s0
	s_addc_u32 s1, s21, 0
	v_ashrrev_i32_e32 v0, 6, v34
	v_and_b32_e32 v84, 15, v34
	s_waitcnt vmcnt(0)
	v_bfe_u32 v119, v34, 4, 2
	s_add_u32 s22, s0, 0x8a14000
	v_readlane_b32 s24, v252, 62
	v_lshlrev_b32_e32 v86, 4, v0
	s_addc_u32 s23, s1, 0
	v_readlane_b32 s25, v252, 63
	v_lshlrev_b32_e32 v118, 2, v119
	v_or_b32_e32 v82, v86, v84
	s_and_b64 s[0:1], s[24:25], exec
	v_cmp_eq_u32_e32 vcc, v118, v82
	v_or_b32_e32 v117, 1, v118
	s_cselect_b32 s7, s7, s23
	s_cselect_b32 s6, s6, s22
	s_and_b64 s[22:23], s[24:25], vcc
	v_cmp_eq_u32_e32 vcc, v117, v82
	v_or_b32_e32 v116, 2, v118
	v_cndmask_b32_e64 v30, 0, 1.0, s[22:23]
	s_and_b64 s[22:23], s[24:25], vcc
	v_cmp_eq_u32_e32 vcc, v116, v82
	v_or_b32_e32 v115, 3, v118
	v_cndmask_b32_e64 v31, 0, 1.0, s[22:23]
	s_and_b64 s[22:23], s[24:25], vcc
	v_cmp_eq_u32_e32 vcc, v115, v82
	v_or_b32_e32 v120, 16, v118
	v_cndmask_b32_e64 v32, 0, 1.0, s[22:23]
	s_and_b64 s[22:23], s[24:25], vcc
	v_cmp_eq_u32_e32 vcc, v120, v82
	v_or_b32_e32 v114, 17, v118
	v_cndmask_b32_e64 v33, 0, 1.0, s[22:23]
	s_and_b64 s[22:23], s[24:25], vcc
	v_cmp_eq_u32_e32 vcc, v114, v82
	v_or_b32_e32 v113, 18, v118
	v_cndmask_b32_e64 v18, 0, 1.0, s[22:23]
	s_and_b64 s[22:23], s[24:25], vcc
	v_cmp_eq_u32_e32 vcc, v113, v82
	v_or_b32_e32 v111, 19, v118
	v_cndmask_b32_e64 v19, 0, 1.0, s[22:23]
	s_and_b64 s[22:23], s[24:25], vcc
	v_cmp_eq_u32_e32 vcc, v111, v82
	v_or_b32_e32 v121, 32, v118
	v_cndmask_b32_e64 v20, 0, 1.0, s[22:23]
	s_and_b64 s[22:23], s[24:25], vcc
	v_cmp_eq_u32_e32 vcc, v121, v82
	v_or_b32_e32 v108, 33, v118
	v_cndmask_b32_e64 v21, 0, 1.0, s[22:23]
	s_and_b64 s[22:23], s[24:25], vcc
	v_cmp_eq_u32_e32 vcc, v108, v82
	v_or_b32_e32 v89, 34, v118
	s_waitcnt vmcnt(0)
	v_cndmask_b32_e64 v10, 0, 1.0, s[22:23]
	s_and_b64 s[22:23], s[24:25], vcc
	v_cmp_eq_u32_e32 vcc, v89, v82
	v_or_b32_e32 v85, 35, v118
	v_cndmask_b32_e64 v11, 0, 1.0, s[22:23]
	s_and_b64 s[22:23], s[24:25], vcc
	v_cmp_eq_u32_e32 vcc, v85, v82
	v_or_b32_e32 v122, 48, v118
	v_cndmask_b32_e64 v12, 0, 1.0, s[22:23]
	s_and_b64 s[22:23], s[24:25], vcc
	v_cmp_eq_u32_e32 vcc, v122, v82
	v_or_b32_e32 v109, 49, v118
	v_cndmask_b32_e64 v13, 0, 1.0, s[22:23]
	s_and_b64 s[22:23], s[24:25], vcc
	v_cmp_eq_u32_e32 vcc, v109, v82
	v_or_b32_e32 v110, 50, v118
	v_cndmask_b32_e64 v2, 0, 1.0, s[22:23]
	s_and_b64 s[22:23], s[24:25], vcc
	v_cmp_eq_u32_e32 vcc, v110, v82
	v_or_b32_e32 v112, 51, v118
	v_cndmask_b32_e64 v3, 0, 1.0, s[22:23]
	s_and_b64 s[22:23], s[24:25], vcc
	v_cmp_eq_u32_e32 vcc, v112, v82
	v_or_b32_e32 v6, 64, v118
	v_cndmask_b32_e64 v4, 0, 1.0, s[22:23]
	s_and_b64 s[22:23], s[24:25], vcc
	v_cmp_eq_u32_e32 vcc, v6, v82
	v_or_b32_e32 v7, 0x41, v118
	v_cndmask_b32_e64 v5, 0, 1.0, s[22:23]
	s_and_b64 s[22:23], s[24:25], vcc
	v_cmp_eq_u32_e32 vcc, v7, v82
	v_or_b32_e32 v8, 0x42, v118
	v_cndmask_b32_e64 v6, 0, 1.0, s[22:23]
	s_and_b64 s[22:23], s[24:25], vcc
	v_cmp_eq_u32_e32 vcc, v8, v82
	v_or_b32_e32 v9, 0x43, v118
	v_cndmask_b32_e64 v7, 0, 1.0, s[22:23]
	s_and_b64 s[22:23], s[24:25], vcc
	v_cmp_eq_u32_e32 vcc, v9, v82
	v_or_b32_e32 v14, 0x50, v118
	v_cndmask_b32_e64 v8, 0, 1.0, s[22:23]
	s_and_b64 s[22:23], s[24:25], vcc
	v_cmp_eq_u32_e32 vcc, v14, v82
	v_or_b32_e32 v15, 0x51, v118
	v_cndmask_b32_e64 v9, 0, 1.0, s[22:23]
	s_and_b64 s[22:23], s[24:25], vcc
	v_cmp_eq_u32_e32 vcc, v15, v82
	v_or_b32_e32 v16, 0x52, v118
	v_cndmask_b32_e64 v14, 0, 1.0, s[22:23]
	s_and_b64 s[22:23], s[24:25], vcc
	v_cmp_eq_u32_e32 vcc, v16, v82
	v_or_b32_e32 v17, 0x53, v118
	v_cndmask_b32_e64 v15, 0, 1.0, s[22:23]
	s_and_b64 s[22:23], s[24:25], vcc
	v_cmp_eq_u32_e32 vcc, v17, v82
	v_or_b32_e32 v22, 0x60, v118
	v_cndmask_b32_e64 v16, 0, 1.0, s[22:23]
	s_and_b64 s[22:23], s[24:25], vcc
	v_cmp_eq_u32_e32 vcc, v22, v82
	v_or_b32_e32 v23, 0x61, v118
	v_cndmask_b32_e64 v17, 0, 1.0, s[22:23]
	s_and_b64 s[22:23], s[24:25], vcc
	v_cmp_eq_u32_e32 vcc, v23, v82
	v_or_b32_e32 v24, 0x62, v118
	v_cndmask_b32_e64 v22, 0, 1.0, s[22:23]
	s_and_b64 s[22:23], s[24:25], vcc
	v_cmp_eq_u32_e32 vcc, v24, v82
	v_or_b32_e32 v25, 0x63, v118
	v_cndmask_b32_e64 v23, 0, 1.0, s[22:23]
	s_and_b64 s[22:23], s[24:25], vcc
	v_cmp_eq_u32_e32 vcc, v25, v82
	v_or_b32_e32 v26, 0x70, v118
	v_cndmask_b32_e64 v24, 0, 1.0, s[22:23]
	s_and_b64 s[22:23], s[24:25], vcc
	v_cmp_eq_u32_e32 vcc, v26, v82
	v_or_b32_e32 v27, 0x71, v118
	v_cndmask_b32_e64 v25, 0, 1.0, s[22:23]
	s_and_b64 s[22:23], s[24:25], vcc
	v_cmp_eq_u32_e32 vcc, v27, v82
	v_or_b32_e32 v28, 0x72, v118
	v_cndmask_b32_e64 v26, 0, 1.0, s[22:23]
	s_and_b64 s[22:23], s[24:25], vcc
	v_cmp_eq_u32_e32 vcc, v28, v82
	v_or_b32_e32 v29, 0x73, v118
	v_cndmask_b32_e64 v27, 0, 1.0, s[22:23]
	s_and_b64 s[22:23], s[24:25], vcc
	v_cmp_eq_u32_e32 vcc, v29, v82
	v_cndmask_b32_e64 v28, 0, 1.0, s[22:23]
	s_and_b64 s[22:23], s[24:25], vcc
	v_readlane_b32 s24, v253, 27
	v_add_u32_e32 v60, 0x200, v34
	v_cndmask_b32_e64 v29, 0, 1.0, s[22:23]
	s_add_u32 s22, s18, s24
	v_ashrrev_i32_e32 v35, 31, v34
	v_ashrrev_i32_e32 v61, 31, v60
	s_addc_u32 s23, s19, 0
	v_lshlrev_b64 v[96:97], 4, v[34:35]
	v_lshlrev_b64 v[94:95], 4, v[60:61]
	v_lshl_add_u64 v[36:37], s[22:23], 0, v[96:97]
	v_lshl_add_u64 v[40:41], s[22:23], 0, v[94:95]
	s_add_u32 s22, s16, s24
	s_load_dwordx2 s[0:1], s[46:47], 0x128
	s_waitcnt lgkmcnt(0)
	s_barrier
; DI void lds_barrier() { asm volatile("s_waitcnt lgkmcnt(0)" ::: "memory"); __builtin_amdgcn_s_barrier(); asm volatile("" ::: "memory"); }
; DI void gdn_scan(CP c, int l, int seq, int h, int mode, unsigned char* sm) {
;     ...
;     lds_barrier();
;     SC_ISSUE(Q, item0); SC_COMMIT(Q, 0);
;     if (nsteps > 1) { SC_ISSUE(P, item0 + 4); SC_ISSUE(Q, item0 + 8); }
;     lds_barrier();
;     for (int n = 0; n < nsteps; n += 2) {
;         SC_STEP(P, n);
;         if (n + 1 < nsteps) SC_STEP(Q, n + 1);
	s_addc_u32 s23, s17, 0
	global_load_dwordx4 v[36:39], v[36:37], off
	v_lshl_add_u64 v[44:45], s[22:23], 0, v[96:97]
	v_lshl_add_u64 v[48:49], s[22:23], 0, v[94:95]
	s_add_u32 s22, s12, s24
	s_addc_u32 s23, s13, 0
	v_lshl_add_u64 v[52:53], s[22:23], 0, v[96:97]
	v_lshl_add_u64 v[56:57], s[22:23], 0, v[94:95]
	global_load_dwordx4 v[40:43], v[40:41], off
	v_readlane_b32 s22, v253, 28
	global_load_dwordx4 v[44:47], v[44:45], off
	v_lshrrev_b32_e32 v62, 4, v34
	global_load_dwordx4 v[48:51], v[48:49], off
	v_mov_b32_e32 v35, s22
	global_load_dwordx4 v[52:55], v[52:53], off
	s_movk_i32 s26, 0x110
	global_load_dwordx4 v[56:59], v[56:57], off
	s_movk_i32 s25, 0x90
	global_load_dword v102, v35, s[8:9]
	v_lshlrev_b32_e32 v35, 4, v34
	v_lshrrev_b32_e32 v34, 3, v34
	v_mul_lo_u32 v83, v62, s26
	v_and_b32_e32 v90, 0xf0, v35
	v_mul_lo_u32 v34, v34, s25
	v_and_b32_e32 v35, 0x70, v35
	v_readlane_b32 s24, v253, 29
	v_add3_u32 v123, 0, v83, v90
	v_add3_u32 v127, 0, v34, v35
	v_lshrrev_b32_e32 v34, 3, v60
	s_add_u32 s22, s18, s24
	v_mul_lo_u32 v34, v34, s25
	s_addc_u32 s23, s19, 0
	v_readlane_b32 s27, v253, 63
	v_add3_u32 v128, 0, v34, v35
	v_lshl_add_u64 v[34:35], s[22:23], 0, v[96:97]
	v_add3_u32 v124, s27, v83, v90
	v_mul_lo_u32 v92, v82, s25
	v_lshlrev_b32_e32 v100, 1, v84
	v_lshlrev_b32_e32 v0, 5, v0
	v_add3_u32 v132, s27, v100, v0
	v_lshlrev_b32_e32 v133, 4, v119
	v_mad_u32_u24 v140, v84, s25, 0
	v_lshlrev_b32_e32 v130, 3, v119
	v_add_u32_e32 v104, 0, v133
	v_mul_u32_u24_e32 v105, 0x110, v84
	v_mul_u32_u24_e32 v106, 0x90, v84
	v_add_u32_e32 v107, 0x1200, v140
	v_add_u32_e32 v141, 0xeb00, v140
	v_mul_u32_u24_e32 v138, 0x440, v119
	v_mul_u32_u24_e32 v139, 0x110, v117
	v_add_u32_e32 v142, v104, v106
	v_add_u32_e32 v143, v107, v133
	s_waitcnt vmcnt(6)
	ds_write_b128 v123, v[36:39]
	v_lshrrev_b32_e32 v36, 4, v60
	v_mul_lo_u32 v91, v36, s26
	v_lshl_add_u64 v[38:39], s[22:23], 0, v[94:95]
	s_add_u32 s22, s16, s24
	v_add3_u32 v125, 0, v91, v90
	v_add3_u32 v126, s27, v91, v90
	s_addc_u32 s23, s17, 0
	global_load_dwordx4 v[34:37], v[34:35], off
	s_waitcnt vmcnt(3)
	ds_write_b128 v124, v[52:55]
	ds_write_b128 v125, v[40:43]
	s_waitcnt vmcnt(2)
	ds_write_b128 v126, v[56:59]
	ds_write_b128 v127, v[44:47] offset:34816
	v_lshl_add_u64 v[42:43], s[22:23], 0, v[96:97]
	v_lshl_add_u64 v[46:47], s[22:23], 0, v[94:95]
	s_add_u32 s22, s12, s24
	s_addc_u32 s23, s13, 0
	ds_write_b128 v128, v[48:51] offset:34816
	v_lshl_add_u64 v[50:51], s[22:23], 0, v[96:97]
	global_load_dwordx4 v[46:49], v[46:47], off
	s_nop 0
	global_load_dwordx4 v[58:61], v[50:51], off
	v_lshl_add_u64 v[50:51], s[22:23], 0, v[94:95]
	v_readlane_b32 s22, v253, 30
	global_load_dwordx4 v[62:65], v[50:51], off
	s_nop 0
	v_mov_b32_e32 v50, s22
	v_readlane_b32 s22, v253, 31
	s_add_u32 s18, s18, s22
	s_addc_u32 s19, s19, 0
	s_add_u32 s16, s16, s22
	s_addc_u32 s17, s17, 0
	s_add_u32 s12, s12, s22
	s_addc_u32 s13, s13, 0
	v_lshl_add_u64 v[74:75], s[12:13], 0, v[96:97]
	v_lshl_add_u64 v[78:79], s[12:13], 0, v[94:95]
	v_readlane_b32 s12, v253, 32
	global_load_dword v88, v50, s[8:9]
	v_lshl_add_u64 v[54:55], s[18:19], 0, v[94:95]
	v_mov_b32_e32 v87, s12
	v_lshl_add_u64 v[66:67], s[16:17], 0, v[96:97]
	v_lshl_add_u64 v[70:71], s[16:17], 0, v[94:95]
	global_load_dword v240, v87, s[8:9]
	v_lshl_add_u64 v[50:51], s[18:19], 0, v[96:97]
	global_load_dwordx4 v[38:41], v[38:39], off
	v_mul_lo_u32 v87, v82, s26
	global_load_dwordx4 v[42:45], v[42:43], off
	s_add_i32 s8, 0, 0x16000
	global_load_dwordx4 v[50:53], v[50:51], off
	v_add_u32_e32 v129, s8, v87
	global_load_dwordx4 v[54:57], v[54:55], off
	v_readlane_b32 s8, v254, 1
	global_load_dwordx4 v[66:69], v[66:67], off
	v_ashrrev_i32_e32 v87, 31, v86
	global_load_dwordx4 v[70:73], v[70:71], off
	v_add_u32_e32 v134, s8, v92
	global_load_dwordx4 v[74:77], v[74:75], off
	v_readlane_b32 s8, v254, 0
	global_load_dwordx4 v[78:81], v[78:79], off
	s_waitcnt lgkmcnt(0)
	s_barrier
	v_add3_u32 v135, s8, v83, v90
	v_add3_u32 v136, s8, v91, v90
	v_add3_u32 v137, s8, v100, v0
	v_readlane_b32 s8, v253, 2
	v_readlane_b32 s9, v253, 3
	v_lshlrev_b32_e32 v0, 10, v119
	v_lshl_add_u64 v[98:99], v[86:87], 1, v[0:1]
	v_lshl_add_u64 v[90:91], s[8:9], 0, v[94:95]
	v_lshl_add_u64 v[92:93], s[8:9], 0, v[96:97]
	v_readlane_b32 s8, v253, 6
	v_readlane_b32 s9, v253, 7
	v_ashrrev_i32_e32 v83, 31, v82
	v_or_b32_e32 v98, v98, v100
	v_lshl_add_u64 v[94:95], s[8:9], 0, v[94:95]
	v_lshl_add_u64 v[96:97], s[8:9], 0, v[96:97]
	v_lshlrev_b64 v[100:101], 8, v[82:83]
	v_readlane_b32 s8, v253, 4
	v_readlane_b32 s12, v253, 0
	v_readlane_b32 s22, v249, 27
	v_add_u32_e32 v131, v129, v130
	v_or_b32_e32 v100, v100, v130
	s_mov_b32 s18, -2
	v_add_u32_e32 v0, v141, v133
	v_add_u32_e32 v141, v104, v105
	v_readlane_b32 s9, v253, 5
	v_readlane_b32 s13, v253, 1
	v_readlane_b32 s23, v249, 28
	s_waitcnt vmcnt(0)
	s_branch .LBB0_552
.LBB0_551:
	s_add_u32 s12, s12, 32
	s_addc_u32 s13, s13, 0
	s_waitcnt lgkmcnt(0)
	s_barrier
	s_mov_b64 s[16:17], 0x20000
	s_add_u32 s8, s8, 32
	v_lshl_add_u64 v[90:91], v[90:91], 0, s[16:17]
	v_lshl_add_u64 v[92:93], v[92:93], 0, s[16:17]
	s_addc_u32 s9, s9, 0
	v_lshl_add_u64 v[94:95], v[94:95], 0, s[16:17]
	v_lshl_add_u64 v[96:97], v[96:97], 0, s[16:17]
	s_mov_b64 s[16:17], 0x40000
	v_lshl_add_u64 v[98:99], v[98:99], 0, s[16:17]
	v_lshl_add_u64 v[100:101], v[100:101], 0, s[16:17]
	s_cmpk_gt_u32 s18, 0x7d
	s_waitcnt vmcnt(8)
	v_mov_b32_e32 v88, v106
	v_mov_b32_e32 v102, v144
	s_cbranch_scc1 .LBB0_620
.LBB0_552:
	v_cndmask_b32_e64 v103, 0, 1, s[22:23]
	v_lshl_add_u64 v[104:105], s[6:7], 0, v[100:101]
	v_cvt_pk_bf16_f32 v106, v30, v31
	v_cvt_pk_bf16_f32 v107, v32, v33
	v_cmp_ne_u32_e64 s[38:39], 1, v103
	s_andn2_b64 vcc, exec, s[22:23]
	s_mov_b64 s[16:17], -1
	ds_write_b64 v131, v[106:107]
	s_cbranch_vccnz .LBB0_554
	s_mov_b64 s[16:17], 0
	global_store_dwordx2 v[104:105], v[106:107], off

.LBB0_584:
	v_add_u32_e32 v103, v132, v138
	v_add_u32_e32 v145, v129, v133
	s_waitcnt lgkmcnt(0)
	v_add_u32_e32 v106, v132, v139
	ds_read_b128 v[146:149], v145
	ds_read_b128 v[150:153], v145 offset:64
	ds_read_b128 v[154:157], v145 offset:128
	ds_read_b128 v[164:167], v145 offset:192
	ds_read_b128 v[172:175], v141
	ds_read_b128 v[176:179], v141 offset:64
	ds_read_b128 v[180:183], v141 offset:128
	ds_read_b128 v[184:187], v141 offset:192
	ds_read_b128 v[214:217], v141 offset:4352
	ds_read_b128 v[218:221], v141 offset:4416
	ds_read_b128 v[222:225], v141 offset:4480
	ds_read_b128 v[226:229], v141 offset:4544
	ds_read_u16 v103, v103
	ds_read_u16 v107, v106
	ds_read_u16 v159, v106 offset:272
	ds_read_u16 v171, v106 offset:544
	ds_read_u16 v192, v106 offset:4080
	ds_read_u16 v193, v106 offset:4352
	ds_read_u16 v204, v106 offset:4624
	ds_read_u16 v205, v106 offset:4896
	ds_read_u16 v206, v106 offset:8432
	ds_read_u16 v207, v106 offset:8704
	ds_read_u16 v213, v106 offset:8976
	ds_read_u16 v230, v106 offset:9248
	ds_read_u16 v231, v106 offset:12784
	ds_read_u16 v232, v106 offset:13056
	ds_read_u16 v233, v106 offset:13328
	ds_read_u16 v234, v106 offset:13600
	s_add_i32 s18, s18, 2
	s_waitcnt lgkmcnt(0)
	v_mfma_f32_16x16x32_bf16 v[172:175], v[172:175], v[146:149], 0
	v_lshlrev_b32_e32 v107, 16, v107
	v_lshlrev_b32_e32 v106, 16, v103
	v_mfma_f32_16x16x32_bf16 v[172:175], v[176:179], v[150:153], v[172:175]
	v_mfma_f32_16x16x32_bf16 v[172:175], v[180:183], v[154:157], v[172:175]
	v_mfma_f32_16x16x32_bf16 v[176:179], v[214:217], v[146:149], 0
	v_mfma_f32_16x16x32_bf16 v[172:175], v[184:187], v[164:167], v[172:175]
	v_mfma_f32_16x16x32_bf16 v[176:179], v[218:221], v[150:153], v[176:179]
	s_nop 6
	v_fma_f32 v106, v168, v106, -v172
	v_fma_f32 v107, v169, v107, -v173
	v_cvt_pk_bf16_f32 v158, v106, v107
	v_lshlrev_b32_e32 v107, 16, v171
	v_lshlrev_b32_e32 v106, 16, v159
	v_pk_fma_f32 v[106:107], v[168:169], v[106:107], v[174:175] neg_lo:[0,0,1] neg_hi:[0,0,1]
	v_mfma_f32_16x16x32_bf16 v[172:175], v[222:225], v[154:157], v[176:179]
	v_cvt_pk_bf16_f32 v159, v106, v107
	v_add_u32_e32 v107, v134, v130
	v_mfma_f32_16x16x32_bf16 v[172:175], v[226:229], v[164:167], v[172:175]
	v_lshlrev_b32_e32 v177, 16, v193
	v_lshlrev_b32_e32 v176, 16, v192
	s_nop 5
	v_pk_fma_f32 v[172:173], v[168:169], v[176:177], v[172:173] neg_lo:[0,0,1] neg_hi:[0,0,1]
	v_lshlrev_b32_e32 v177, 16, v205
	v_lshlrev_b32_e32 v176, 16, v204
	v_pk_fma_f32 v[174:175], v[168:169], v[176:177], v[174:175] neg_lo:[0,0,1] neg_hi:[0,0,1]
	v_cvt_pk_bf16_f32 v172, v172, v173
	v_cvt_pk_bf16_f32 v173, v174, v175
	ds_write2_b64 v107, v[158:159], v[172:173] offset1:4
	ds_read_b128 v[172:175], v141 offset:8704
	ds_read_b128 v[176:179], v141 offset:8768
	ds_read_b128 v[180:183], v141 offset:8832
	ds_read_b128 v[184:187], v141 offset:8896
	ds_read_b128 v[214:217], v141 offset:13056
	ds_read_b128 v[218:221], v141 offset:13120
	ds_read_b128 v[222:225], v141 offset:13184
	ds_read_b128 v[226:229], v141 offset:13248
	s_waitcnt lgkmcnt(7)
	v_mfma_f32_16x16x32_bf16 v[172:175], v[172:175], v[146:149], 0
	v_lshlrev_b32_e32 v159, 16, v207
	v_lshlrev_b32_e32 v158, 16, v206
	s_waitcnt lgkmcnt(3)
	v_mfma_f32_16x16x32_bf16 v[146:149], v[214:217], v[146:149], 0
	v_mfma_f32_16x16x32_bf16 v[172:175], v[176:179], v[150:153], v[172:175]
	s_waitcnt lgkmcnt(2)
	v_mfma_f32_16x16x32_bf16 v[146:149], v[218:221], v[150:153], v[146:149]
	v_lshlrev_b32_e32 v151, 16, v230
	v_lshlrev_b32_e32 v150, 16, v213
	v_mfma_f32_16x16x32_bf16 v[172:175], v[180:183], v[154:157], v[172:175]
	s_waitcnt lgkmcnt(1)
	v_mfma_f32_16x16x32_bf16 v[146:149], v[222:225], v[154:157], v[146:149]
	v_mfma_f32_16x16x32_bf16 v[172:175], v[184:187], v[164:167], v[172:175]
	s_waitcnt lgkmcnt(0)
	v_mfma_f32_16x16x32_bf16 v[146:149], v[226:229], v[164:167], v[146:149]
	s_nop 5
	v_fma_f32 v158, v168, v158, -v172
	v_fma_f32 v159, v169, v159, -v173
	v_pk_fma_f32 v[150:151], v[168:169], v[150:151], v[174:175] neg_lo:[0,0,1] neg_hi:[0,0,1]
	v_cvt_pk_bf16_f32 v158, v158, v159
	v_cvt_pk_bf16_f32 v159, v150, v151
	v_lshlrev_b32_e32 v151, 16, v232
	v_lshlrev_b32_e32 v150, 16, v231
	v_pk_fma_f32 v[146:147], v[168:169], v[150:151], v[146:147] neg_lo:[0,0,1] neg_hi:[0,0,1]
	v_lshlrev_b32_e32 v151, 16, v234
	v_lshlrev_b32_e32 v150, 16, v233
	v_pk_fma_f32 v[148:149], v[168:169], v[150:151], v[148:149] neg_lo:[0,0,1] neg_hi:[0,0,1]
	v_cvt_pk_bf16_f32 v146, v146, v147
	v_cvt_pk_bf16_f32 v147, v148, v149
	ds_write2_b64 v107, v[158:159], v[146:147] offset0:8 offset1:12
	ds_read_b128 v[148:151], v142 offset:34816
	ds_read_b128 v[152:155], v142 offset:34880
	ds_read_b128 v[156:159], v142 offset:37120
	ds_read_b128 v[164:167], v142 offset:37184
	ds_read_b128 v[172:175], v142 offset:39424
	ds_read_b128 v[176:179], v142 offset:39488
	ds_read_b128 v[180:183], v142 offset:41728
	ds_read_b128 v[184:187], v142 offset:41792
	v_add_u32_e32 v146, v134, v133
	s_waitcnt lgkmcnt(0)
	ds_read_b128 v[214:217], v146 offset:64
	ds_read_b128 v[218:221], v146
	v_pk_mul_f32 v[32:33], v[102:103], v[32:33] op_sel_hi:[0,1]
	v_pk_mul_f32 v[30:31], v[102:103], v[30:31] op_sel_hi:[0,1]
	v_pk_mul_f32 v[20:21], v[102:103], v[20:21] op_sel_hi:[0,1]
	v_pk_mul_f32 v[18:19], v[102:103], v[18:19] op_sel_hi:[0,1]
	v_pk_mul_f32 v[12:13], v[102:103], v[12:13] op_sel_hi:[0,1]
	v_pk_mul_f32 v[10:11], v[102:103], v[10:11] op_sel_hi:[0,1]
	v_pk_mul_f32 v[4:5], v[102:103], v[4:5] op_sel_hi:[0,1]
	v_pk_mul_f32 v[2:3], v[102:103], v[2:3] op_sel_hi:[0,1]
	s_waitcnt lgkmcnt(0)
	v_mfma_f32_16x16x32_bf16 v[30:33], v[148:151], v[218:221], v[30:33]
	v_mfma_f32_16x16x32_bf16 v[18:21], v[156:159], v[218:221], v[18:21]
	v_mfma_f32_16x16x32_bf16 v[10:13], v[172:175], v[218:221], v[10:13]
	v_mfma_f32_16x16x32_bf16 v[2:5], v[180:183], v[218:221], v[2:5]
	v_mfma_f32_16x16x32_bf16 v[30:33], v[152:155], v[214:217], v[30:33]
	v_mfma_f32_16x16x32_bf16 v[18:21], v[164:167], v[214:217], v[18:21]
	v_mfma_f32_16x16x32_bf16 v[10:13], v[176:179], v[214:217], v[10:13]
	v_mfma_f32_16x16x32_bf16 v[2:5], v[184:187], v[214:217], v[2:5]
	v_add_u32_e32 v147, v140, v133
	ds_read_b128 v[148:151], v147 offset:51008
	ds_read_b128 v[152:155], v147 offset:50944
	ds_read_b128 v[156:159], v143 offset:44096
	ds_read_b128 v[164:167], v143 offset:44032
	ds_read_b128 v[172:175], v147 offset:46400
	ds_read_b128 v[176:179], v147 offset:46336
	ds_read_b128 v[180:183], v147 offset:44096
	ds_read_b128 v[184:187], v147 offset:44032
	v_pk_mul_f32 v[8:9], v[102:103], v[8:9] op_sel_hi:[0,1]
	v_pk_mul_f32 v[6:7], v[102:103], v[6:7] op_sel_hi:[0,1]
	v_pk_mul_f32 v[16:17], v[102:103], v[16:17] op_sel_hi:[0,1]
	v_pk_mul_f32 v[14:15], v[102:103], v[14:15] op_sel_hi:[0,1]
	v_pk_mul_f32 v[24:25], v[102:103], v[24:25] op_sel_hi:[0,1]
	v_pk_mul_f32 v[22:23], v[102:103], v[22:23] op_sel_hi:[0,1]
	v_pk_mul_f32 v[28:29], v[102:103], v[28:29] op_sel_hi:[0,1]
	v_pk_mul_f32 v[26:27], v[102:103], v[26:27] op_sel_hi:[0,1]
	s_waitcnt lgkmcnt(0)
	v_mfma_f32_16x16x32_bf16 v[6:9], v[184:187], v[218:221], v[6:9]
	v_mfma_f32_16x16x32_bf16 v[14:17], v[176:179], v[218:221], v[14:17]
	v_mfma_f32_16x16x32_bf16 v[22:25], v[164:167], v[218:221], v[22:25]
	v_mfma_f32_16x16x32_bf16 v[26:29], v[152:155], v[218:221], v[26:29]
	v_mfma_f32_16x16x32_bf16 v[6:9], v[180:183], v[214:217], v[6:9]
	v_mfma_f32_16x16x32_bf16 v[14:17], v[172:175], v[214:217], v[14:17]
	v_mfma_f32_16x16x32_bf16 v[22:25], v[156:159], v[214:217], v[22:25]
	v_mfma_f32_16x16x32_bf16 v[26:29], v[148:151], v[214:217], v[26:29]
	s_cmpk_gt_u32 s18, 0x7c
	v_mov_b32_e32 v106, v88
	s_waitcnt vmcnt(16)
	ds_write_b128 v123, v[34:37] offset:17408
	ds_write_b128 v135, v[58:61]
	s_waitcnt vmcnt(7)
	ds_write_b128 v125, v[38:41] offset:17408
	ds_write_b128 v136, v[62:65]
	s_waitcnt vmcnt(6)
	ds_write_b128 v127, v[42:45] offset:53248
	ds_write_b128 v128, v[46:49] offset:53248
	s_cbranch_scc1 .LBB0_586
	v_lshl_add_u64 v[58:59], s[20:21], 0, v[96:97]
	v_add_co_u32_e32 v34, vcc, 0x156c4000, v58
	v_lshl_add_u64 v[60:61], s[20:21], 0, v[94:95]
	s_nop 0
	v_addc_co_u32_e32 v35, vcc, 0, v59, vcc
	v_add_co_u32_e32 v38, vcc, 0x156c4000, v60
	s_add_u32 s16, s20, s8
	s_nop 0
	v_addc_co_u32_e32 v39, vcc, 0, v61, vcc
	v_add_co_u32_e32 v42, vcc, 0x17ac4000, v58
	s_addc_u32 s17, s21, s9
	s_nop 0
	v_addc_co_u32_e32 v43, vcc, 0, v59, vcc
	v_add_co_u32_e32 v46, vcc, 0x17ac4000, v60
	global_load_dwordx4 v[34:37], v[34:35], off
	s_nop 0
	global_load_dwordx4 v[38:41], v[38:39], off
	v_addc_co_u32_e32 v47, vcc, 0, v61, vcc
	v_add_co_u32_e32 v58, vcc, 0x144c4000, v58
	global_load_dwordx4 v[42:45], v[42:43], off
	s_nop 0
	global_load_dwordx4 v[46:49], v[46:47], off
	v_addc_co_u32_e32 v59, vcc, 0, v59, vcc
	v_add_co_u32_e32 v62, vcc, 0x144c4000, v60
	s_nop 1
	v_addc_co_u32_e32 v63, vcc, 0, v61, vcc
	global_load_dwordx4 v[58:61], v[58:59], off
	s_nop 0
	global_load_dwordx4 v[62:65], v[62:63], off
	s_nop 0
	global_load_dword v106, v1, s[16:17]

.LBB0_618:
	v_add_u32_e32 v171, v137, v138
	v_add_u32_e32 v192, v137, v139
	s_waitcnt lgkmcnt(0)
	ds_read_b128 v[102:105], v145
	ds_read_b128 v[148:151], v145 offset:64
	ds_read_b128 v[152:155], v145 offset:128
	ds_read_b128 v[156:159], v145 offset:192
	ds_read_b128 v[164:167], v141 offset:17408
	ds_read_b128 v[172:175], v141 offset:17472
	ds_read_b128 v[176:179], v141 offset:17536
	ds_read_b128 v[180:183], v141 offset:17600
	ds_read_b128 v[184:187], v141 offset:21760
	ds_read_b128 v[214:217], v141 offset:21824
	ds_read_b128 v[218:221], v141 offset:21888
	ds_read_b128 v[222:225], v141 offset:21952
	ds_read_u16 v145, v171
	ds_read_u16 v171, v192
	ds_read_u16 v193, v192 offset:272
	ds_read_u16 v204, v192 offset:544
	ds_read_u16 v205, v192 offset:4080
	ds_read_u16 v206, v192 offset:4352
	ds_read_u16 v207, v192 offset:4624
	ds_read_u16 v213, v192 offset:4896
	ds_read_u16 v226, v192 offset:8432
	ds_read_u16 v227, v192 offset:8704
	ds_read_u16 v228, v192 offset:8976
	ds_read_u16 v229, v192 offset:9248
	ds_read_u16 v230, v192 offset:12784
	ds_read_u16 v231, v192 offset:13056
	ds_read_u16 v232, v192 offset:13328
	ds_read_u16 v192, v192 offset:13600
	s_waitcnt lgkmcnt(14)
	v_mfma_f32_16x16x32_bf16 v[164:167], v[164:167], v[102:105], 0
	v_mfma_f32_16x16x32_bf16 v[164:167], v[172:175], v[148:151], v[164:167]
	v_mfma_f32_16x16x32_bf16 v[164:167], v[176:179], v[152:155], v[164:167]
	v_lshlrev_b32_e32 v177, 16, v171
	v_lshlrev_b32_e32 v176, 16, v145
	v_mfma_f32_16x16x32_bf16 v[172:175], v[184:187], v[102:105], 0
	v_mfma_f32_16x16x32_bf16 v[164:167], v[180:183], v[156:159], v[164:167]
	v_mfma_f32_16x16x32_bf16 v[172:175], v[214:217], v[148:151], v[172:175]
	s_nop 6
	v_fma_f32 v164, v168, v176, -v164
	v_fma_f32 v165, v169, v177, -v165
	v_cvt_pk_bf16_f32 v176, v164, v165
	s_waitcnt lgkmcnt(12)
	v_lshlrev_b32_e32 v165, 16, v204
	v_lshlrev_b32_e32 v164, 16, v193
	v_pk_fma_f32 v[178:179], v[168:169], v[164:165], v[166:167] neg_lo:[0,0,1] neg_hi:[0,0,1]
	v_mfma_f32_16x16x32_bf16 v[164:167], v[218:221], v[152:155], v[172:175]
	v_cvt_pk_bf16_f32 v177, v178, v179
	v_mfma_f32_16x16x32_bf16 v[164:167], v[222:225], v[156:159], v[164:167]
	s_waitcnt lgkmcnt(10)
	v_lshlrev_b32_e32 v173, 16, v206
	v_lshlrev_b32_e32 v172, 16, v205
	s_nop 4
	v_pk_fma_f32 v[164:165], v[168:169], v[172:173], v[164:165] neg_lo:[0,0,1] neg_hi:[0,0,1]
	s_waitcnt lgkmcnt(8)
	v_lshlrev_b32_e32 v173, 16, v213
	v_lshlrev_b32_e32 v172, 16, v207
	v_pk_fma_f32 v[166:167], v[168:169], v[172:173], v[166:167] neg_lo:[0,0,1] neg_hi:[0,0,1]
	v_cvt_pk_bf16_f32 v164, v164, v165
	v_cvt_pk_bf16_f32 v165, v166, v167
	ds_write2_b64 v107, v[176:177], v[164:165] offset1:4
	ds_read_b128 v[164:167], v141 offset:26112
	ds_read_b128 v[172:175], v141 offset:26176
	ds_read_b128 v[176:179], v141 offset:26240
	ds_read_b128 v[180:183], v141 offset:26304
	ds_read_b128 v[184:187], v141 offset:30464
	ds_read_b128 v[214:217], v141 offset:30528
	ds_read_b128 v[218:221], v141 offset:30592
	ds_read_b128 v[222:225], v141 offset:30656
	s_waitcnt lgkmcnt(7)
	v_mfma_f32_16x16x32_bf16 v[164:167], v[164:167], v[102:105], 0
	s_waitcnt lgkmcnt(3)
	v_mfma_f32_16x16x32_bf16 v[102:105], v[184:187], v[102:105], 0
	v_mfma_f32_16x16x32_bf16 v[164:167], v[172:175], v[148:151], v[164:167]
	v_lshlrev_b32_e32 v173, 16, v227
	v_lshlrev_b32_e32 v172, 16, v226
	s_waitcnt lgkmcnt(2)
	v_mfma_f32_16x16x32_bf16 v[102:105], v[214:217], v[148:151], v[102:105]
	v_lshlrev_b32_e32 v149, 16, v229
	v_lshlrev_b32_e32 v148, 16, v228
	v_mfma_f32_16x16x32_bf16 v[164:167], v[176:179], v[152:155], v[164:167]
	s_waitcnt lgkmcnt(1)
	v_mfma_f32_16x16x32_bf16 v[102:105], v[218:221], v[152:155], v[102:105]
	v_mfma_f32_16x16x32_bf16 v[164:167], v[180:183], v[156:159], v[164:167]
	s_waitcnt lgkmcnt(0)
	v_mfma_f32_16x16x32_bf16 v[102:105], v[222:225], v[156:159], v[102:105]
	s_nop 5
	v_fma_f32 v164, v168, v172, -v164
	v_fma_f32 v165, v169, v173, -v165
	v_pk_fma_f32 v[148:149], v[168:169], v[148:149], v[166:167] neg_lo:[0,0,1] neg_hi:[0,0,1]
	v_cvt_pk_bf16_f32 v164, v164, v165
	v_cvt_pk_bf16_f32 v165, v148, v149
	v_lshlrev_b32_e32 v149, 16, v231
	v_lshlrev_b32_e32 v148, 16, v230
	v_pk_fma_f32 v[102:103], v[168:169], v[148:149], v[102:103] neg_lo:[0,0,1] neg_hi:[0,0,1]
	v_lshlrev_b32_e32 v149, 16, v192
	v_lshlrev_b32_e32 v148, 16, v232
	v_pk_fma_f32 v[104:105], v[168:169], v[148:149], v[104:105] neg_lo:[0,0,1] neg_hi:[0,0,1]
	v_cvt_pk_bf16_f32 v102, v102, v103
	v_cvt_pk_bf16_f32 v103, v104, v105
	ds_write2_b64 v107, v[164:165], v[102:103] offset0:8 offset1:12
	ds_read_b128 v[102:105], v142 offset:53248
	ds_read_b128 v[148:151], v142 offset:53312
	ds_read_b128 v[152:155], v142 offset:55552
	ds_read_b128 v[156:159], v142 offset:55616
	ds_read_b128 v[164:167], v142 offset:57856
	ds_read_b128 v[172:175], v142 offset:57920
	ds_read_b128 v[176:179], v142 offset:60160
	ds_read_b128 v[180:183], v142 offset:60224
	s_waitcnt lgkmcnt(0)
	ds_read_b128 v[184:187], v146 offset:64
	ds_read_b128 v[214:217], v146
	v_pk_mul_f32 v[32:33], v[88:89], v[32:33] op_sel_hi:[0,1]
	v_pk_mul_f32 v[30:31], v[88:89], v[30:31] op_sel_hi:[0,1]
	v_pk_mul_f32 v[20:21], v[88:89], v[20:21] op_sel_hi:[0,1]
	v_pk_mul_f32 v[18:19], v[88:89], v[18:19] op_sel_hi:[0,1]
	v_pk_mul_f32 v[12:13], v[88:89], v[12:13] op_sel_hi:[0,1]
	v_pk_mul_f32 v[10:11], v[88:89], v[10:11] op_sel_hi:[0,1]
	v_pk_mul_f32 v[4:5], v[88:89], v[4:5] op_sel_hi:[0,1]
	v_pk_mul_f32 v[2:3], v[88:89], v[2:3] op_sel_hi:[0,1]
	s_waitcnt lgkmcnt(0)
	v_mfma_f32_16x16x32_bf16 v[30:33], v[102:105], v[214:217], v[30:33]
	v_mfma_f32_16x16x32_bf16 v[18:21], v[152:155], v[214:217], v[18:21]
	v_mfma_f32_16x16x32_bf16 v[10:13], v[164:167], v[214:217], v[10:13]
	v_mfma_f32_16x16x32_bf16 v[2:5], v[176:179], v[214:217], v[2:5]
	v_mfma_f32_16x16x32_bf16 v[30:33], v[148:151], v[184:187], v[30:33]
	v_mfma_f32_16x16x32_bf16 v[18:21], v[156:159], v[184:187], v[18:21]
	v_mfma_f32_16x16x32_bf16 v[10:13], v[172:175], v[184:187], v[10:13]
	v_mfma_f32_16x16x32_bf16 v[2:5], v[180:183], v[184:187], v[2:5]
	ds_read_b128 v[102:105], v0 offset:9280
	ds_read_b128 v[148:151], v0 offset:9216
	ds_read_b128 v[152:155], v143 offset:62528
	ds_read_b128 v[156:159], v143 offset:62464
	ds_read_b128 v[164:167], v147 offset:64832
	ds_read_b128 v[172:175], v147 offset:64768
	ds_read_b128 v[176:179], v147 offset:62528
	ds_read_b128 v[180:183], v147 offset:62464
	v_pk_mul_f32 v[8:9], v[88:89], v[8:9] op_sel_hi:[0,1]
	v_pk_mul_f32 v[6:7], v[88:89], v[6:7] op_sel_hi:[0,1]
	v_pk_mul_f32 v[16:17], v[88:89], v[16:17] op_sel_hi:[0,1]
	v_pk_mul_f32 v[14:15], v[88:89], v[14:15] op_sel_hi:[0,1]
	v_pk_mul_f32 v[24:25], v[88:89], v[24:25] op_sel_hi:[0,1]
	v_pk_mul_f32 v[22:23], v[88:89], v[22:23] op_sel_hi:[0,1]
	v_pk_mul_f32 v[28:29], v[88:89], v[28:29] op_sel_hi:[0,1]
	v_pk_mul_f32 v[26:27], v[88:89], v[26:27] op_sel_hi:[0,1]
	s_waitcnt lgkmcnt(0)
	v_mfma_f32_16x16x32_bf16 v[6:9], v[180:183], v[214:217], v[6:9]
	v_mfma_f32_16x16x32_bf16 v[14:17], v[172:175], v[214:217], v[14:17]
	v_mfma_f32_16x16x32_bf16 v[22:25], v[156:159], v[214:217], v[22:25]
	v_mfma_f32_16x16x32_bf16 v[26:29], v[148:151], v[214:217], v[26:29]
	v_mfma_f32_16x16x32_bf16 v[6:9], v[176:179], v[184:187], v[6:9]
	v_mfma_f32_16x16x32_bf16 v[14:17], v[164:167], v[184:187], v[14:17]
	v_mfma_f32_16x16x32_bf16 v[22:25], v[152:155], v[184:187], v[22:25]
	v_mfma_f32_16x16x32_bf16 v[26:29], v[102:105], v[184:187], v[26:29]
	s_cmpk_gt_u32 s18, 0x7b
	s_waitcnt vmcnt(16)
	v_mov_b32_e32 v144, v240
	ds_write_b128 v123, v[50:53]
	ds_write_b128 v124, v[74:77]
	ds_write_b128 v125, v[54:57]
	ds_write_b128 v126, v[78:81]
	ds_write_b128 v127, v[66:69] offset:34816
	ds_write_b128 v128, v[70:73] offset:34816
	s_cbranch_scc1 .LBB0_551
	v_lshl_add_u64 v[74:75], s[20:21], 0, v[92:93]
	v_add_co_u32_e32 v50, vcc, 0x156c4000, v74
	v_lshl_add_u64 v[76:77], s[20:21], 0, v[90:91]
	s_nop 0
	v_addc_co_u32_e32 v51, vcc, 0, v75, vcc
	v_add_co_u32_e32 v54, vcc, 0x156c4000, v76
	s_add_u32 s16, s20, s12
	s_nop 0
	v_addc_co_u32_e32 v55, vcc, 0, v77, vcc
	v_add_co_u32_e32 v66, vcc, 0x17ac4000, v74
	s_addc_u32 s17, s21, s13
	s_nop 0
	v_addc_co_u32_e32 v67, vcc, 0, v75, vcc
	v_add_co_u32_e32 v70, vcc, 0x17ac4000, v76
	global_load_dwordx4 v[50:53], v[50:51], off
	s_nop 0
	global_load_dwordx4 v[54:57], v[54:55], off
	v_addc_co_u32_e32 v71, vcc, 0, v77, vcc
	v_add_co_u32_e32 v74, vcc, 0x144c4000, v74
	global_load_dwordx4 v[66:69], v[66:67], off
	s_nop 0
	global_load_dwordx4 v[70:73], v[70:71], off
	v_addc_co_u32_e32 v75, vcc, 0, v75, vcc
	v_add_co_u32_e32 v78, vcc, 0x144c4000, v76
	s_nop 1
	v_addc_co_u32_e32 v79, vcc, 0, v77, vcc
	global_load_dwordx4 v[74:77], v[74:75], off
	s_nop 0
	global_load_dwordx4 v[78:81], v[78:79], off
	s_nop 0
	global_load_dword v240, v1, s[16:17]
	s_branch .LBB0_551
